# v43 with the P0 bf16 packs moved under the QK2 tail, V s=1 reads before the first check, second-half packs under the P.V MFMAs
# baseline (speedup 1.0000x reference)
.Lm_noload:
	s_cmp_gt_i32 s20, s35
	s_cbranch_scc1 .LBB0_379
	s_bitcmp1_b32 s20, 0
	s_cselect_b32 s38, 0xb400, 0
	v_add_u32_e32 v8, s38, v191
	ds_read_b128 v[10:13], v8
	ds_read_b128 v[14:17], v8 offset:32
	ds_read_b128 v[202:205], v8 offset:64
	ds_read_b128 v[206:209], v8 offset:96
	v_add_u32_e32 v197, s38, v196
	s_setprio 3
	s_waitcnt lgkmcnt(3)
	v_mfma_f32_32x32x16_bf16 v[100:115], v[10:13], v[116:119], v[210:225]
	ds_read_b128 v[10:13], v8 offset:128
	s_waitcnt lgkmcnt(3)
	v_mfma_f32_32x32x16_bf16 v[100:115], v[14:17], v[120:123], v[100:115]
	ds_read_b128 v[14:17], v8 offset:160
	s_waitcnt lgkmcnt(3)
	v_mfma_f32_32x32x16_bf16 v[100:115], v[202:205], v[124:127], v[100:115]
	ds_read_b128 v[202:205], v8 offset:192
	s_waitcnt lgkmcnt(3)
	v_mfma_f32_32x32x16_bf16 v[100:115], v[206:209], v[132:135], v[100:115]
	ds_read_b128 v[206:209], v8 offset:224
	s_waitcnt lgkmcnt(3)
	v_mfma_f32_32x32x16_bf16 v[100:115], v[10:13], v[136:139], v[100:115]
	ds_read_b128 v[10:13], v8 offset:256
	s_waitcnt lgkmcnt(3)
	v_mfma_f32_32x32x16_bf16 v[100:115], v[14:17], v[140:143], v[100:115]
	ds_read_b128 v[14:17], v8 offset:288
	s_waitcnt lgkmcnt(3)
	v_mfma_f32_32x32x16_bf16 v[100:115], v[202:205], v[144:147], v[100:115]
	ds_read_b128 v[202:205], v8 offset:320
	s_waitcnt lgkmcnt(3)
	v_mfma_f32_32x32x16_bf16 v[100:115], v[206:209], v[148:151], v[100:115]
	ds_read_b128 v[206:209], v8 offset:352
	s_waitcnt lgkmcnt(3)
	v_mfma_f32_32x32x16_bf16 v[100:115], v[10:13], v[152:155], v[100:115]
	ds_read_b128 v[10:13], v8 offset:12800
	s_waitcnt lgkmcnt(3)
	v_mfma_f32_32x32x16_bf16 v[100:115], v[14:17], v[156:159], v[100:115]
	ds_read_b128 v[14:17], v8 offset:12832
	s_waitcnt lgkmcnt(3)
	v_mfma_f32_32x32x16_bf16 v[100:115], v[202:205], v[160:163], v[100:115]
	ds_read_b128 v[202:205], v8 offset:12864
	s_waitcnt lgkmcnt(3)
	v_mfma_f32_32x32x16_bf16 v[100:115], v[206:209], v[164:167], v[100:115]
	ds_read_b128 v[206:209], v8 offset:12896
	s_waitcnt lgkmcnt(3)
	v_mfma_f32_32x32x16_bf16 v[84:99], v[10:13], v[116:119], v[210:225]
	ds_read_b128 v[10:13], v8 offset:12928
	s_waitcnt lgkmcnt(3)
	v_mfma_f32_32x32x16_bf16 v[84:99], v[14:17], v[120:123], v[84:99]
	ds_read_b128 v[14:17], v8 offset:12960
	s_waitcnt lgkmcnt(3)
	v_mfma_f32_32x32x16_bf16 v[84:99], v[202:205], v[124:127], v[84:99]
	ds_read_b128 v[202:205], v8 offset:12992
	s_waitcnt lgkmcnt(3)
	v_mfma_f32_32x32x16_bf16 v[84:99], v[206:209], v[132:135], v[84:99]
	ds_read_b128 v[206:209], v8 offset:13024
	s_waitcnt lgkmcnt(3)
	v_mfma_f32_32x32x16_bf16 v[84:99], v[10:13], v[136:139], v[84:99]
	ds_read_b128 v[10:13], v8 offset:13056
	v_exp_f32_e32 v100, v100
	v_exp_f32_e32 v101, v101
	s_waitcnt lgkmcnt(3)
	v_mfma_f32_32x32x16_bf16 v[84:99], v[14:17], v[140:143], v[84:99]
	ds_read_b128 v[14:17], v8 offset:13088
	v_exp_f32_e32 v102, v102
	v_exp_f32_e32 v103, v103
	v_add_f32_e32 v234, 0, v100
	v_add_f32_e32 v234, v101, v234
	s_waitcnt lgkmcnt(3)
	v_mfma_f32_32x32x16_bf16 v[84:99], v[202:205], v[144:147], v[84:99]
	ds_read_b128 v[202:205], v8 offset:13120
	v_exp_f32_e32 v104, v104
	v_exp_f32_e32 v105, v105
	v_add_f32_e32 v234, v102, v234
	v_add_f32_e32 v234, v103, v234
	s_waitcnt lgkmcnt(3)
	v_mfma_f32_32x32x16_bf16 v[84:99], v[206:209], v[148:151], v[84:99]
	ds_read_b128 v[206:209], v8 offset:13152
	v_exp_f32_e32 v106, v106
	v_exp_f32_e32 v107, v107
	v_add_f32_e32 v234, v104, v234
	v_add_f32_e32 v234, v105, v234
	s_waitcnt lgkmcnt(3)
	v_mfma_f32_32x32x16_bf16 v[84:99], v[10:13], v[152:155], v[84:99]
	ds_read_b64_tr_b16 v[10:11], v197 offset:25600
	ds_read_b64_tr_b16 v[12:13], v197 offset:28160
	v_exp_f32_e32 v108, v108
	v_exp_f32_e32 v109, v109
	v_add_f32_e32 v234, v106, v234
	v_add_f32_e32 v234, v107, v234
	s_waitcnt lgkmcnt(4)
	v_mfma_f32_32x32x16_bf16 v[84:99], v[14:17], v[156:159], v[84:99]
	ds_read_b64_tr_b16 v[14:15], v197 offset:25664
	ds_read_b64_tr_b16 v[16:17], v197 offset:28224
	v_exp_f32_e32 v110, v110
	v_exp_f32_e32 v111, v111
	v_add_f32_e32 v234, v108, v234
	v_add_f32_e32 v234, v109, v234
	s_waitcnt lgkmcnt(5)
	v_mfma_f32_32x32x16_bf16 v[84:99], v[202:205], v[160:163], v[84:99]
	ds_read_b64_tr_b16 v[202:203], v197 offset:25728
	ds_read_b64_tr_b16 v[204:205], v197 offset:28288
	v_exp_f32_e32 v112, v112
	v_exp_f32_e32 v113, v113
	v_add_f32_e32 v234, v110, v234
	v_add_f32_e32 v234, v111, v234
	v_cvt_pk_bf16_f32 v226, v100, v101
	v_cvt_pk_bf16_f32 v227, v102, v103
	v_cvt_pk_bf16_f32 v228, v104, v105
	v_cvt_pk_bf16_f32 v229, v106, v107
	s_waitcnt lgkmcnt(6)
	v_mfma_f32_32x32x16_bf16 v[84:99], v[206:209], v[164:167], v[84:99]
	ds_read_b64_tr_b16 v[206:207], v197 offset:25792
	ds_read_b64_tr_b16 v[208:209], v197 offset:28352
	v_exp_f32_e32 v114, v114
	v_exp_f32_e32 v115, v115
	v_add_f32_e32 v234, v112, v234
	v_add_f32_e32 v234, v113, v234
	v_cvt_pk_bf16_f32 v230, v108, v109
	v_cvt_pk_bf16_f32 v231, v110, v111
	v_cvt_pk_bf16_f32 v232, v112, v113
	v_cvt_pk_bf16_f32 v233, v114, v115
	v_add_f32_e32 v234, v114, v234
	v_add_f32_e32 v234, v115, v234
	ds_read_b64_tr_b16 v[100:101], v197 offset:30720
	ds_read_b64_tr_b16 v[102:103], v197 offset:33280
	ds_read_b64_tr_b16 v[104:105], v197 offset:30784
	ds_read_b64_tr_b16 v[106:107], v197 offset:33344
	ds_read_b64_tr_b16 v[108:109], v197 offset:30848
	ds_read_b64_tr_b16 v[110:111], v197 offset:33408
	ds_read_b64_tr_b16 v[112:113], v197 offset:30912
	ds_read_b64_tr_b16 v[114:115], v197 offset:33472
	s_and_b64 vcc, exec, s[18:19]
	s_cbranch_vccz .Lm_p1
	s_setprio 0
	s_branch .Lm_pd

.Lm_pd:
	v_cmp_lt_f32_e32 vcc, 0x47800000, v234
	s_cbranch_vccnz .Lm_RA
	v_add_f32_e32 v193, v193, v234
	s_waitcnt lgkmcnt(14)
	v_mfma_f32_32x32x16_bf16 v[68:83], v[10:13], v[226:229], v[68:83]
	v_exp_f32_e32 v84, v84
	v_exp_f32_e32 v85, v85
	v_exp_f32_e32 v86, v86
	v_exp_f32_e32 v87, v87
	s_waitcnt lgkmcnt(12)
	v_mfma_f32_32x32x16_bf16 v[52:67], v[14:17], v[226:229], v[52:67]
	v_exp_f32_e32 v88, v88
	v_exp_f32_e32 v89, v89
	v_exp_f32_e32 v90, v90
	v_exp_f32_e32 v91, v91
	s_waitcnt lgkmcnt(10)
	v_mfma_f32_32x32x16_bf16 v[36:51], v[202:205], v[226:229], v[36:51]
	v_exp_f32_e32 v92, v92
	v_exp_f32_e32 v93, v93
	v_exp_f32_e32 v94, v94
	v_exp_f32_e32 v95, v95
	s_waitcnt lgkmcnt(8)
	v_mfma_f32_32x32x16_bf16 v[20:35], v[206:209], v[226:229], v[20:35]
	v_exp_f32_e32 v96, v96
	v_exp_f32_e32 v97, v97
	v_exp_f32_e32 v98, v98
	v_exp_f32_e32 v99, v99
	ds_read_b64_tr_b16 v[10:11], v197 offset:35840
	ds_read_b64_tr_b16 v[12:13], v197 offset:38400
	ds_read_b64_tr_b16 v[14:15], v197 offset:35904
	ds_read_b64_tr_b16 v[16:17], v197 offset:38464
	ds_read_b64_tr_b16 v[202:203], v197 offset:35968
	ds_read_b64_tr_b16 v[204:205], v197 offset:38528
	ds_read_b64_tr_b16 v[206:207], v197 offset:36032
	ds_read_b64_tr_b16 v[208:209], v197 offset:38592
	s_waitcnt lgkmcnt(14)
	v_mfma_f32_32x32x16_bf16 v[68:83], v[100:103], v[230:233], v[68:83]
	v_add_f32_e32 v240, 0, v84
	v_add_f32_e32 v240, v85, v240
	v_add_f32_e32 v240, v86, v240
	v_add_f32_e32 v240, v87, v240
	v_cvt_pk_bf16_f32 v226, v84, v85
	s_waitcnt lgkmcnt(12)
	v_mfma_f32_32x32x16_bf16 v[52:67], v[104:107], v[230:233], v[52:67]
	v_add_f32_e32 v240, v88, v240
	v_add_f32_e32 v240, v89, v240
	v_add_f32_e32 v240, v90, v240
	v_add_f32_e32 v240, v91, v240
	v_cvt_pk_bf16_f32 v227, v86, v87
	s_waitcnt lgkmcnt(10)
	v_mfma_f32_32x32x16_bf16 v[36:51], v[108:111], v[230:233], v[36:51]
	v_add_f32_e32 v240, v92, v240
	v_add_f32_e32 v240, v93, v240
	v_add_f32_e32 v240, v94, v240
	v_add_f32_e32 v240, v95, v240
	v_cvt_pk_bf16_f32 v228, v88, v89
	s_waitcnt lgkmcnt(8)
	v_mfma_f32_32x32x16_bf16 v[20:35], v[112:115], v[230:233], v[20:35]
	v_add_f32_e32 v240, v96, v240
	v_add_f32_e32 v240, v97, v240
	v_add_f32_e32 v240, v98, v240
	v_add_f32_e32 v240, v99, v240
	v_cvt_pk_bf16_f32 v229, v90, v91
	ds_read_b64_tr_b16 v[100:101], v197 offset:40960
	ds_read_b64_tr_b16 v[102:103], v197 offset:43520
	ds_read_b64_tr_b16 v[104:105], v197 offset:41024
	ds_read_b64_tr_b16 v[106:107], v197 offset:43584
	ds_read_b64_tr_b16 v[108:109], v197 offset:41088
	ds_read_b64_tr_b16 v[110:111], v197 offset:43648
	ds_read_b64_tr_b16 v[112:113], v197 offset:41152
	ds_read_b64_tr_b16 v[114:115], v197 offset:43712
	v_cmp_lt_f32_e32 vcc, 0x47800000, v240
	s_cbranch_vccnz .Lm_RB
.Lm_postB:
	v_add_f32_e32 v193, v193, v240
	v_cvt_pk_bf16_f32 v230, v92, v93
	v_cvt_pk_bf16_f32 v231, v94, v95
	v_cvt_pk_bf16_f32 v232, v96, v97
	v_cvt_pk_bf16_f32 v233, v98, v99
	s_waitcnt lgkmcnt(14)
	v_mfma_f32_32x32x16_bf16 v[68:83], v[10:13], v[226:229], v[68:83]
	s_waitcnt lgkmcnt(12)
	v_mfma_f32_32x32x16_bf16 v[52:67], v[14:17], v[226:229], v[52:67]
	s_waitcnt lgkmcnt(10)
	v_mfma_f32_32x32x16_bf16 v[36:51], v[202:205], v[226:229], v[36:51]
	s_waitcnt lgkmcnt(8)
	v_mfma_f32_32x32x16_bf16 v[20:35], v[206:209], v[226:229], v[20:35]
	s_waitcnt lgkmcnt(6)
	v_mfma_f32_32x32x16_bf16 v[68:83], v[100:103], v[230:233], v[68:83]
	s_waitcnt lgkmcnt(4)
	v_mfma_f32_32x32x16_bf16 v[52:67], v[104:107], v[230:233], v[52:67]
	s_waitcnt lgkmcnt(2)
	v_mfma_f32_32x32x16_bf16 v[36:51], v[108:111], v[230:233], v[36:51]
	s_waitcnt lgkmcnt(0)
	v_mfma_f32_32x32x16_bf16 v[20:35], v[112:115], v[230:233], v[20:35]

.Lm_RB:
	s_waitcnt lgkmcnt(0)
	ds_read_b128 v[10:13], v8 offset:12800
	ds_read_b128 v[14:17], v8 offset:12832
	ds_read_b128 v[202:205], v8 offset:12864
	ds_read_b128 v[206:209], v8 offset:12896
	s_waitcnt lgkmcnt(3)
	v_mfma_f32_32x32x16_bf16 v[84:99], v[10:13], v[116:119], v[210:225]
	ds_read_b128 v[10:13], v8 offset:12928
	s_waitcnt lgkmcnt(3)
	v_mfma_f32_32x32x16_bf16 v[84:99], v[14:17], v[120:123], v[84:99]
	ds_read_b128 v[14:17], v8 offset:12960
	s_waitcnt lgkmcnt(3)
	v_mfma_f32_32x32x16_bf16 v[84:99], v[202:205], v[124:127], v[84:99]
	ds_read_b128 v[202:205], v8 offset:12992
	s_waitcnt lgkmcnt(3)
	v_mfma_f32_32x32x16_bf16 v[84:99], v[206:209], v[132:135], v[84:99]
	ds_read_b128 v[206:209], v8 offset:13024
	s_waitcnt lgkmcnt(3)
	v_mfma_f32_32x32x16_bf16 v[84:99], v[10:13], v[136:139], v[84:99]
	ds_read_b128 v[10:13], v8 offset:13056
	s_waitcnt lgkmcnt(3)
	v_mfma_f32_32x32x16_bf16 v[84:99], v[14:17], v[140:143], v[84:99]
	ds_read_b128 v[14:17], v8 offset:13088
	s_waitcnt lgkmcnt(3)
	v_mfma_f32_32x32x16_bf16 v[84:99], v[202:205], v[144:147], v[84:99]
	ds_read_b128 v[202:205], v8 offset:13120
	s_waitcnt lgkmcnt(3)
	v_mfma_f32_32x32x16_bf16 v[84:99], v[206:209], v[148:151], v[84:99]
	ds_read_b128 v[206:209], v8 offset:13152
	s_waitcnt lgkmcnt(3)
	v_mfma_f32_32x32x16_bf16 v[84:99], v[10:13], v[152:155], v[84:99]
	s_waitcnt lgkmcnt(2)
	v_mfma_f32_32x32x16_bf16 v[84:99], v[14:17], v[156:159], v[84:99]
	s_waitcnt lgkmcnt(1)
	v_mfma_f32_32x32x16_bf16 v[84:99], v[202:205], v[160:163], v[84:99]
	s_waitcnt lgkmcnt(0)
	v_mfma_f32_32x32x16_bf16 v[84:99], v[206:209], v[164:167], v[84:99]
	s_nop 11
	v_max3_f32 v235, v84, v85, v86
	v_max3_f32 v235, v235, v87, v88
	v_max3_f32 v235, v235, v89, v90
	v_max3_f32 v235, v235, v91, v92
	v_max3_f32 v235, v235, v93, v94
	v_max3_f32 v235, v235, v95, v96
	v_max3_f32 v235, v235, v97, v98
	v_max3_f32 v235, v235, v99, v99
	v_mov_b32_e32 v237, v235
	v_mov_b32_e32 v239, v235
	s_nop 1
	v_permlane32_swap_b32_e32 v237, v239
	v_cndmask_b32_e64 v237, v237, v239, s[4:5]
	v_max_f32_e32 v237, v237, v237
	v_max_f32_e32 v236, v235, v237
	v_max_f32_e32 v236, 0, v236
	v_exp_f32_e64 v238, -v236
	v_pk_add_f32 v[84:85], v[84:85], v[236:237] op_sel_hi:[1,0] neg_lo:[0,1] neg_hi:[0,1]
	v_pk_add_f32 v[86:87], v[86:87], v[236:237] op_sel_hi:[1,0] neg_lo:[0,1] neg_hi:[0,1]
	v_pk_add_f32 v[88:89], v[88:89], v[236:237] op_sel_hi:[1,0] neg_lo:[0,1] neg_hi:[0,1]
	v_pk_add_f32 v[90:91], v[90:91], v[236:237] op_sel_hi:[1,0] neg_lo:[0,1] neg_hi:[0,1]
	v_pk_add_f32 v[92:93], v[92:93], v[236:237] op_sel_hi:[1,0] neg_lo:[0,1] neg_hi:[0,1]
	v_pk_add_f32 v[94:95], v[94:95], v[236:237] op_sel_hi:[1,0] neg_lo:[0,1] neg_hi:[0,1]
	v_pk_add_f32 v[96:97], v[96:97], v[236:237] op_sel_hi:[1,0] neg_lo:[0,1] neg_hi:[0,1]
	v_pk_add_f32 v[98:99], v[98:99], v[236:237] op_sel_hi:[1,0] neg_lo:[0,1] neg_hi:[0,1]
	v_pk_add_f32 v[210:211], v[210:211], v[236:237] op_sel_hi:[1,0] neg_lo:[0,1] neg_hi:[0,1]
	v_pk_add_f32 v[212:213], v[212:213], v[236:237] op_sel_hi:[1,0] neg_lo:[0,1] neg_hi:[0,1]
	v_pk_add_f32 v[214:215], v[214:215], v[236:237] op_sel_hi:[1,0] neg_lo:[0,1] neg_hi:[0,1]
	v_pk_add_f32 v[216:217], v[216:217], v[236:237] op_sel_hi:[1,0] neg_lo:[0,1] neg_hi:[0,1]
	v_pk_add_f32 v[218:219], v[218:219], v[236:237] op_sel_hi:[1,0] neg_lo:[0,1] neg_hi:[0,1]
	v_pk_add_f32 v[220:221], v[220:221], v[236:237] op_sel_hi:[1,0] neg_lo:[0,1] neg_hi:[0,1]
	v_pk_add_f32 v[222:223], v[222:223], v[236:237] op_sel_hi:[1,0] neg_lo:[0,1] neg_hi:[0,1]
	v_pk_add_f32 v[224:225], v[224:225], v[236:237] op_sel_hi:[1,0] neg_lo:[0,1] neg_hi:[0,1]
	v_mul_f32_e32 v193, v193, v238
	v_pk_mul_f32 v[68:69], v[68:69], v[238:239] op_sel_hi:[1,0]
	v_pk_mul_f32 v[70:71], v[70:71], v[238:239] op_sel_hi:[1,0]
	v_pk_mul_f32 v[72:73], v[72:73], v[238:239] op_sel_hi:[1,0]
	v_pk_mul_f32 v[74:75], v[74:75], v[238:239] op_sel_hi:[1,0]
	v_pk_mul_f32 v[76:77], v[76:77], v[238:239] op_sel_hi:[1,0]
	v_pk_mul_f32 v[78:79], v[78:79], v[238:239] op_sel_hi:[1,0]
	v_pk_mul_f32 v[80:81], v[80:81], v[238:239] op_sel_hi:[1,0]
	v_pk_mul_f32 v[82:83], v[82:83], v[238:239] op_sel_hi:[1,0]
	v_pk_mul_f32 v[52:53], v[52:53], v[238:239] op_sel_hi:[1,0]
	v_pk_mul_f32 v[54:55], v[54:55], v[238:239] op_sel_hi:[1,0]
	v_pk_mul_f32 v[56:57], v[56:57], v[238:239] op_sel_hi:[1,0]
	v_pk_mul_f32 v[58:59], v[58:59], v[238:239] op_sel_hi:[1,0]
	v_pk_mul_f32 v[60:61], v[60:61], v[238:239] op_sel_hi:[1,0]
	v_pk_mul_f32 v[62:63], v[62:63], v[238:239] op_sel_hi:[1,0]
	v_pk_mul_f32 v[64:65], v[64:65], v[238:239] op_sel_hi:[1,0]
	v_pk_mul_f32 v[66:67], v[66:67], v[238:239] op_sel_hi:[1,0]
	v_pk_mul_f32 v[36:37], v[36:37], v[238:239] op_sel_hi:[1,0]
	v_pk_mul_f32 v[38:39], v[38:39], v[238:239] op_sel_hi:[1,0]
	v_pk_mul_f32 v[40:41], v[40:41], v[238:239] op_sel_hi:[1,0]
	v_pk_mul_f32 v[42:43], v[42:43], v[238:239] op_sel_hi:[1,0]
	v_pk_mul_f32 v[44:45], v[44:45], v[238:239] op_sel_hi:[1,0]
	v_pk_mul_f32 v[46:47], v[46:47], v[238:239] op_sel_hi:[1,0]
	v_pk_mul_f32 v[48:49], v[48:49], v[238:239] op_sel_hi:[1,0]
	v_pk_mul_f32 v[50:51], v[50:51], v[238:239] op_sel_hi:[1,0]
	v_pk_mul_f32 v[20:21], v[20:21], v[238:239] op_sel_hi:[1,0]
	v_pk_mul_f32 v[22:23], v[22:23], v[238:239] op_sel_hi:[1,0]
	v_pk_mul_f32 v[24:25], v[24:25], v[238:239] op_sel_hi:[1,0]
	v_pk_mul_f32 v[26:27], v[26:27], v[238:239] op_sel_hi:[1,0]
	v_pk_mul_f32 v[28:29], v[28:29], v[238:239] op_sel_hi:[1,0]
	v_pk_mul_f32 v[30:31], v[30:31], v[238:239] op_sel_hi:[1,0]
	v_pk_mul_f32 v[32:33], v[32:33], v[238:239] op_sel_hi:[1,0]
	v_pk_mul_f32 v[34:35], v[34:35], v[238:239] op_sel_hi:[1,0]
	v_add_f32_e32 v192, v192, v236
	v_exp_f32_e32 v84, v84
	v_exp_f32_e32 v85, v85
	v_exp_f32_e32 v86, v86
	v_exp_f32_e32 v87, v87
	v_exp_f32_e32 v88, v88
	v_exp_f32_e32 v89, v89
	v_exp_f32_e32 v90, v90
	v_exp_f32_e32 v91, v91
	v_exp_f32_e32 v92, v92
	v_exp_f32_e32 v93, v93
	v_exp_f32_e32 v94, v94
	v_exp_f32_e32 v95, v95
	v_exp_f32_e32 v96, v96
	v_exp_f32_e32 v97, v97
	v_exp_f32_e32 v98, v98
	v_exp_f32_e32 v99, v99
	v_add_f32_e32 v240, 0, v84
	v_add_f32_e32 v240, v85, v240
	v_add_f32_e32 v240, v86, v240
	v_add_f32_e32 v240, v87, v240
	v_add_f32_e32 v240, v88, v240
	v_add_f32_e32 v240, v89, v240
	v_add_f32_e32 v240, v90, v240
	v_add_f32_e32 v240, v91, v240
	v_add_f32_e32 v240, v92, v240
	v_add_f32_e32 v240, v93, v240
	v_add_f32_e32 v240, v94, v240
	v_add_f32_e32 v240, v95, v240
	v_add_f32_e32 v240, v96, v240
	v_add_f32_e32 v240, v97, v240
	v_add_f32_e32 v240, v98, v240
	v_add_f32_e32 v240, v99, v240
	v_cvt_pk_bf16_f32 v226, v84, v85
	v_cvt_pk_bf16_f32 v227, v86, v87
	v_cvt_pk_bf16_f32 v228, v88, v89
	v_cvt_pk_bf16_f32 v229, v90, v91
	ds_read_b64_tr_b16 v[10:11], v197 offset:35840
	ds_read_b64_tr_b16 v[12:13], v197 offset:38400
	ds_read_b64_tr_b16 v[14:15], v197 offset:35904
	ds_read_b64_tr_b16 v[16:17], v197 offset:38464
	ds_read_b64_tr_b16 v[202:203], v197 offset:35968
	ds_read_b64_tr_b16 v[204:205], v197 offset:38528
	ds_read_b64_tr_b16 v[206:207], v197 offset:36032
	ds_read_b64_tr_b16 v[208:209], v197 offset:38592
	s_waitcnt lgkmcnt(0)
	s_branch .Lm_postB
